# speedup vs baseline: 1.0028x; 1.0028x over previous
; DI unsigned pk_bf16(float lo, float hi) { f32x2_t v = {lo, hi}; return __builtin_bit_cast(unsigned, __builtin_convertvector(v, bf16x2_t)); }
; DI void cvt_rows(const float* __restrict__ src, u16* __restrict__ dst, size_t n) {
;     ...
;   for (; i + 3 * T < nv; i += 4 * T) {
;     f32x4 a[4], b[4];
; #pragma unroll
;     for (int u = 0; u < 4; ++u) { a[u] = *(const f32x4*)(src + (i + u * T) * 8); b[u] = *(const f32x4*)(src + (i + u * T) * 8 + 4); }
; #pragma unroll
;     for (int u = 0; u < 4; ++u) {
;       u32x4 o; o[0] = pk_bf16(a[u][0], a[u][1]); o[1] = pk_bf16(a[u][2], a[u][3]); o[2] = pk_bf16(b[u][0], b[u][1]); o[3] = pk_bf16(b[u][2], b[u][3]);
;       *(u32x4*)(dst + (i + u * T) * 8) = o;
;     }
;   }
.LBB0_92:
	global_load_dwordx4 v[12:15], v[10:11], off
	global_load_dwordx4 v[16:19], v[10:11], off offset:16
	v_lshl_add_u64 v[28:29], v[10:11], 0, s[46:47]
	global_load_dwordx4 v[20:23], v[28:29], off
	global_load_dwordx4 v[24:27], v[28:29], off offset:16
	v_lshl_add_u64 v[36:37], v[28:29], 0, s[46:47]
	global_load_dwordx4 v[28:31], v[36:37], off
	global_load_dwordx4 v[32:35], v[36:37], off offset:16
	v_lshl_add_u64 v[40:41], v[36:37], 0, s[46:47]
	global_load_dwordx4 v[36:39], v[40:41], off
	s_nop 0
	global_load_dwordx4 v[40:43], v[40:41], off offset:16
	s_add_u32 s2, s36, s36
	s_addc_u32 s3, s37, s37
	s_add_u32 s2, s2, s2
	s_addc_u32 s3, s3, s3
	v_lshl_add_u64 v[44:45], s[28:29], 0, v[2:3]
	v_lshl_add_u64 v[0:1], s[2:3], 0, v[0:1]
	v_lshl_add_u64 v[46:47], s[28:29], 0, v[8:9]
	v_lshl_add_u64 v[48:49], s[28:29], 0, v[4:5]
	v_lshl_add_u64 v[50:51], s[28:29], 0, v[6:7]
	s_add_u32 s28, s28, s38
	v_lshl_add_u64 v[52:53], s[42:43], 0, v[0:1]
	s_addc_u32 s29, s29, s39
	v_cmp_lt_u64_e32 vcc, s[48:49], v[52:53]
	v_lshl_add_u64 v[10:11], v[10:11], 0, s[44:45]
	s_or_b64 s[22:23], vcc, s[22:23]
	s_waitcnt vmcnt(7)
	v_cvt_pk_bf16_f32 v12, v12, v13
	v_cvt_pk_bf16_f32 v13, v14, v15
	s_waitcnt vmcnt(6)
	v_cvt_pk_bf16_f32 v14, v16, v17
	v_cvt_pk_bf16_f32 v15, v18, v19
	global_store_dwordx4 v[44:45], v[12:15], off sc0 sc1
	s_waitcnt vmcnt(6)
	s_nop 0
	v_cvt_pk_bf16_f32 v12, v20, v21
	v_cvt_pk_bf16_f32 v13, v22, v23
	s_waitcnt vmcnt(5)
	v_cvt_pk_bf16_f32 v14, v24, v25
	v_cvt_pk_bf16_f32 v15, v26, v27
	global_store_dwordx4 v[46:47], v[12:15], off sc0 sc1
	s_waitcnt vmcnt(5)
	s_nop 0
	v_cvt_pk_bf16_f32 v12, v28, v29
	v_cvt_pk_bf16_f32 v13, v30, v31
	s_waitcnt vmcnt(4)
	v_cvt_pk_bf16_f32 v14, v32, v33
	v_cvt_pk_bf16_f32 v15, v34, v35
	global_store_dwordx4 v[48:49], v[12:15], off sc0 sc1
	s_waitcnt vmcnt(4)
	s_nop 0
	v_cvt_pk_bf16_f32 v12, v36, v37
	v_cvt_pk_bf16_f32 v13, v38, v39
	s_waitcnt vmcnt(3)
	v_cvt_pk_bf16_f32 v14, v40, v41
	v_cvt_pk_bf16_f32 v15, v42, v43
	global_store_dwordx4 v[50:51], v[12:15], off sc0 sc1
	s_andn2_b64 exec, exec, s[22:23]
	s_cbranch_execnz .LBB0_92
	s_or_b64 exec, exec, s[22:23]

; DI unsigned pk_bf16(float lo, float hi) { f32x2_t v = {lo, hi}; return __builtin_bit_cast(unsigned, __builtin_convertvector(v, bf16x2_t)); }
; DI void cvt_rows(const float* __restrict__ src, u16* __restrict__ dst, size_t n) {
;     ...
;   for (; i < nv; i += T) {
;     const f32x4 a = *(const f32x4*)(src + i * 8), b = *(const f32x4*)(src + i * 8 + 4);
;     u32x4 o; o[0] = pk_bf16(a[0], a[1]); o[1] = pk_bf16(a[2], a[3]); o[2] = pk_bf16(b[0], b[1]); o[3] = pk_bf16(b[2], b[3]);
;     *(u32x4*)(dst + i * 8) = o;
;   }
.LBB0_96:
	global_load_dwordx4 v[6:9], v[2:3], off offset:-16
	global_load_dwordx4 v[10:13], v[2:3], off
	v_lshl_add_u64 v[0:1], v[0:1], 0, s[28:29]
	v_cmp_lt_u64_e32 vcc, s[42:43], v[0:1]
	v_lshl_add_u64 v[2:3], v[2:3], 0, s[36:37]
	s_or_b64 s[22:23], vcc, s[22:23]
	s_waitcnt vmcnt(1)
	v_cvt_pk_bf16_f32 v6, v6, v7
	v_cvt_pk_bf16_f32 v7, v8, v9
	s_waitcnt vmcnt(0)
	v_cvt_pk_bf16_f32 v8, v10, v11
	v_cvt_pk_bf16_f32 v9, v12, v13
	global_store_dwordx4 v[4:5], v[6:9], off sc0 sc1
	v_lshl_add_u64 v[4:5], v[4:5], 0, s[38:39]
	s_andn2_b64 exec, exec, s[22:23]
	s_cbranch_execnz .LBB0_96

; #define SLOAD(uq, dq, c0) _Pragma("unroll") for (int i = 0; i < 32; ++i) { uq[i] = U[(size_t)((c0) + i) * 64]; dq[i] = dv[(size_t)((c0) + i) * 512]; }
; #define SSCAN(uq, dq, c0) _Pragma("unroll") for (int i = 0; i < 32; ++i) { ST[(size_t)((c0) + i) * 64] = (u16)pk_bf16(st, 0.f); st = dq[i] * st + bf2f(uq[i]); }
; DI void scan_phase(const Params& p) {
;     ...
;     float st = 0.f;
;     u16 ua[32], ub[32]; float da[32], db[32];
;     ...
;     SLOAD(ua, da, 0)
;     for (int c0 = 0; c0 < 256; c0 += 64) {
;       SLOAD(ub, db, c0 + 32)
;       SSCAN(ua, da, c0)
;       if (c0 + 64 < 256) SLOAD(ua, da, c0 + 64)
;       SSCAN(ub, db, c0 + 32)
;     }
.LBB0_851:
	v_and_b32_e32 v14, 0xffff0000, v36
	s_mov_b32 s3, 0xca81000
	v_fmac_f32_e32 v14, v33, v130
	v_add_co_u32_e32 v10, vcc, s3, v10
	v_cvt_pk_bf16_f32 v15, v14, s0
	s_nop 0
	v_addc_co_u32_e32 v11, vcc, 0, v11, vcc
	global_store_short v[10:11], v15, off sc0 sc1
	v_lshlrev_b32_e32 v15, 16, v42
	v_fmac_f32_e32 v15, v50, v14
	v_cvt_pk_bf16_f32 v14, v15, s0
	global_store_short v[10:11], v14, off offset:128 sc0 sc1
	v_lshlrev_b32_e32 v14, 16, v49
	v_fmac_f32_e32 v14, v48, v15
	v_cvt_pk_bf16_f32 v15, v14, s0
	global_store_short v[10:11], v15, off offset:256 sc0 sc1
	v_lshlrev_b32_e32 v15, 16, v47
	s_waitcnt vmcnt(62)
	v_fmac_f32_e32 v15, v46, v14
	v_cvt_pk_bf16_f32 v14, v15, s0
	global_store_short v[10:11], v14, off offset:384 sc0 sc1
	v_lshlrev_b32_e32 v14, 16, v45
	v_fmac_f32_e32 v14, v44, v15
	v_cvt_pk_bf16_f32 v15, v14, s0
	global_store_short v[10:11], v15, off offset:512 sc0 sc1
	v_lshlrev_b32_e32 v15, 16, v43
	v_fmac_f32_e32 v15, v53, v14
	v_cvt_pk_bf16_f32 v14, v15, s0
	global_store_short v[10:11], v14, off offset:640 sc0 sc1
	v_lshlrev_b32_e32 v14, 16, v58
	v_fmac_f32_e32 v14, v55, v15
	v_cvt_pk_bf16_f32 v15, v14, s0
	global_store_short v[10:11], v15, off offset:768 sc0 sc1
	v_lshlrev_b32_e32 v15, 16, v59
	v_fmac_f32_e32 v15, v56, v14
	v_cvt_pk_bf16_f32 v14, v15, s0
	global_store_short v[10:11], v14, off offset:896 sc0 sc1
	v_lshlrev_b32_e32 v14, 16, v60
	v_fmac_f32_e32 v14, v57, v15
	v_cvt_pk_bf16_f32 v15, v14, s0
	global_store_short v[10:11], v15, off offset:1024 sc0 sc1
	v_lshlrev_b32_e32 v15, 16, v54
	v_fmac_f32_e32 v15, v68, v14
	v_cvt_pk_bf16_f32 v14, v15, s0
	global_store_short v[10:11], v14, off offset:1152 sc0 sc1
	v_lshlrev_b32_e32 v14, 16, v66
	v_fmac_f32_e32 v14, v63, v15
	v_cvt_pk_bf16_f32 v15, v14, s0
	global_store_short v[10:11], v15, off offset:1280 sc0 sc1
	v_lshlrev_b32_e32 v15, 16, v62
	v_fmac_f32_e32 v15, v73, v14
	v_cvt_pk_bf16_f32 v14, v15, s0
	global_store_short v[10:11], v14, off offset:1408 sc0 sc1
	v_lshlrev_b32_e32 v14, 16, v70
	v_fmac_f32_e32 v14, v69, v15
	v_cvt_pk_bf16_f32 v15, v14, s0
	global_store_short v[10:11], v15, off offset:1536 sc0 sc1
	v_lshlrev_b32_e32 v15, 16, v67
	v_fmac_f32_e32 v15, v75, v14
	v_cvt_pk_bf16_f32 v14, v15, s0
	global_store_short v[10:11], v14, off offset:1664 sc0 sc1
	v_lshlrev_b32_e32 v14, 16, v81
	v_fmac_f32_e32 v14, v77, v15
	v_cvt_pk_bf16_f32 v15, v14, s0
	global_store_short v[10:11], v15, off offset:1792 sc0 sc1
	v_lshlrev_b32_e32 v15, 16, v82
	v_fmac_f32_e32 v15, v78, v14
	v_cvt_pk_bf16_f32 v14, v15, s0
	global_store_short v[10:11], v14, off offset:1920 sc0 sc1
	v_lshlrev_b32_e32 v14, 16, v83
	v_fmac_f32_e32 v14, v79, v15
	v_cvt_pk_bf16_f32 v15, v14, s0
	global_store_short v[10:11], v15, off offset:2048 sc0 sc1
	v_lshlrev_b32_e32 v15, 16, v76
	v_fmac_f32_e32 v15, v90, v14
	v_cvt_pk_bf16_f32 v14, v15, s0
	global_store_short v[10:11], v14, off offset:2176 sc0 sc1
	v_lshlrev_b32_e32 v14, 16, v89
	v_fmac_f32_e32 v14, v88, v15
	v_cvt_pk_bf16_f32 v15, v14, s0
	global_store_short v[10:11], v15, off offset:2304 sc0 sc1
	v_lshlrev_b32_e32 v15, 16, v87
	s_waitcnt vmcnt(62)
	v_fmac_f32_e32 v15, v86, v14
	v_cvt_pk_bf16_f32 v14, v15, s0
	global_store_short v[10:11], v14, off offset:2432 sc0 sc1
	v_lshlrev_b32_e32 v14, 16, v85
	v_fmac_f32_e32 v14, v84, v15
	v_cvt_pk_bf16_f32 v15, v14, s0
	global_store_short v[10:11], v15, off offset:2560 sc0 sc1
	v_lshlrev_b32_e32 v15, 16, v80
	v_fmac_f32_e32 v15, v92, v14
	v_cvt_pk_bf16_f32 v14, v15, s0
	global_store_short v[10:11], v14, off offset:2688 sc0 sc1
	v_lshlrev_b32_e32 v14, 16, v98
	v_fmac_f32_e32 v14, v94, v15
	v_cvt_pk_bf16_f32 v15, v14, s0
	global_store_short v[10:11], v15, off offset:2816 sc0 sc1
	v_lshlrev_b32_e32 v15, 16, v99
	v_fmac_f32_e32 v15, v95, v14
	v_cvt_pk_bf16_f32 v14, v15, s0
	global_store_short v[10:11], v14, off offset:2944 sc0 sc1
	v_lshlrev_b32_e32 v14, 16, v100
	v_fmac_f32_e32 v14, v96, v15
	v_cvt_pk_bf16_f32 v15, v14, s0
	global_store_short v[10:11], v15, off offset:3072 sc0 sc1
	v_lshlrev_b32_e32 v15, 16, v93
	v_fmac_f32_e32 v15, v111, v14
	v_cvt_pk_bf16_f32 v14, v15, s0
	global_store_short v[10:11], v14, off offset:3200 sc0 sc1
	v_lshlrev_b32_e32 v14, 16, v109
	v_fmac_f32_e32 v14, v107, v15
	v_cvt_pk_bf16_f32 v15, v14, s0
	global_store_short v[10:11], v15, off offset:3328 sc0 sc1
	v_lshlrev_b32_e32 v15, 16, v105
	s_waitcnt vmcnt(62)
	v_fmac_f32_e32 v15, v104, v14
	v_cvt_pk_bf16_f32 v14, v15, s0
	global_store_short v[10:11], v14, off offset:3456 sc0 sc1
	v_lshlrev_b32_e32 v14, 16, v102
	v_fmac_f32_e32 v14, v101, v15
	v_cvt_pk_bf16_f32 v15, v14, s0
	global_store_short v[10:11], v15, off offset:3584 sc0 sc1
	v_lshlrev_b32_e32 v15, 16, v97
	v_fmac_f32_e32 v15, v124, v14
	v_cvt_pk_bf16_f32 v14, v15, s0
	global_store_short v[10:11], v14, off offset:3712 sc0 sc1
	v_lshlrev_b32_e32 v14, 16, v122
	v_fmac_f32_e32 v14, v125, v15
	v_cvt_pk_bf16_f32 v15, v14, s0
	global_store_short v[10:11], v15, off offset:3840 sc0 sc1
	v_lshlrev_b32_e32 v15, 16, v127
	s_mov_b64 s[36:37], 0x20000
	s_waitcnt vmcnt(62)
	v_fmac_f32_e32 v15, v126, v14
	v_lshlrev_b32_e32 v130, 16, v128
	v_lshl_add_u64 v[8:9], v[8:9], 0, s[36:37]
	s_mov_b64 s[36:37], 0x2000
	s_add_i32 s2, s2, 64
	v_cvt_pk_bf16_f32 v14, v15, s0
	v_fmac_f32_e32 v130, v129, v15
	v_lshl_add_u64 v[6:7], v[6:7], 0, s[36:37]
	s_and_b64 vcc, exec, s[28:29]
	s_waitcnt vmcnt(31)
	v_mov_b32_e32 v33, v12
	v_mov_b32_e32 v36, v13
	global_store_short v[10:11], v14, off offset:3968 sc0 sc1
	s_cbranch_vccnz .LBB0_848
; #define SLOAD(uq, dq, c0) _Pragma("unroll") for (int i = 0; i < 32; ++i) { uq[i] = U[(size_t)((c0) + i) * 64]; dq[i] = dv[(size_t)((c0) + i) * 512]; }
; #define SSCAN(uq, dq, c0) _Pragma("unroll") for (int i = 0; i < 32; ++i) { ST[(size_t)((c0) + i) * 64] = (u16)pk_bf16(st, 0.f); st = dq[i] * st + bf2f(uq[i]); }
; DI void scan_phase(const Params& p) {
;     ...
;     SLOAD(ua, da, 0)
;     for (int c0 = 0; c0 < 256; c0 += 64) {
;       SLOAD(ub, db, c0 + 32)
;       SSCAN(ua, da, c0)
;       if (c0 + 64 < 256) SLOAD(ua, da, c0 + 64)
;       SSCAN(ub, db, c0 + 32)
.LBB0_852:
	v_lshl_add_u64 v[10:11], s[90:91], 0, v[6:7]
	s_mov_b32 s3, 0x8a01000
	v_add_co_u32_e32 v14, vcc, s3, v10
	v_lshl_add_u64 v[12:13], s[90:91], 0, v[8:9]
	s_nop 0
	v_addc_co_u32_e32 v15, vcc, 0, v11, vcc
	s_mov_b32 s3, 0xaa10000
	v_add_co_u32_e32 v44, vcc, s3, v12
	s_mov_b32 s3, 0xaa11000
	s_nop 0
	v_addc_co_u32_e32 v45, vcc, 0, v13, vcc
	v_add_co_u32_e32 v54, vcc, s3, v12
	s_mov_b32 s3, 0xaa12000
	s_nop 0
	v_addc_co_u32_e32 v55, vcc, 0, v13, vcc
	global_load_ushort v42, v[14:15], off
	global_load_dword v50, v[54:55], off offset:-4096
	global_load_ushort v49, v[14:15], off offset:128
	global_load_dword v48, v[44:45], off offset:2048
	global_load_ushort v47, v[14:15], off offset:256
	global_load_dword v46, v[54:55], off
	s_nop 0
	global_load_ushort v45, v[14:15], off offset:384
	global_load_dword v44, v[54:55], off offset:2048
	global_load_ushort v43, v[14:15], off offset:512
	v_add_co_u32_e32 v54, vcc, s3, v12
	s_mov_b32 s3, 0xaa13000
	s_nop 0
	v_addc_co_u32_e32 v55, vcc, 0, v13, vcc
	v_add_co_u32_e32 v62, vcc, s3, v12
	s_mov_b32 s3, 0xaa14000
	s_nop 0
	v_addc_co_u32_e32 v63, vcc, 0, v13, vcc
	global_load_dword v53, v[62:63], off offset:-4096
	global_load_ushort v58, v[14:15], off offset:640
	s_nop 0
	global_load_dword v55, v[54:55], off offset:2048
	s_nop 0
	global_load_ushort v59, v[14:15], off offset:768
	global_load_dword v56, v[62:63], off
	global_load_ushort v60, v[14:15], off offset:896
	global_load_dword v57, v[62:63], off offset:2048
	global_load_ushort v54, v[14:15], off offset:1024
	v_add_co_u32_e32 v62, vcc, s3, v12
	s_mov_b32 s3, 0xaa15000
	s_nop 0
	v_addc_co_u32_e32 v63, vcc, 0, v13, vcc
	v_add_co_u32_e32 v76, vcc, s3, v12
	s_mov_b32 s3, 0xaa16000
	s_nop 0
	v_addc_co_u32_e32 v77, vcc, 0, v13, vcc
	global_load_dword v68, v[76:77], off offset:-4096
	global_load_ushort v66, v[14:15], off offset:1152
	s_nop 0
	global_load_dword v63, v[62:63], off offset:2048
	s_nop 0
	global_load_ushort v62, v[14:15], off offset:1280
	global_load_dword v73, v[76:77], off
	global_load_ushort v70, v[14:15], off offset:1408
	global_load_dword v69, v[76:77], off offset:2048
	global_load_ushort v67, v[14:15], off offset:1536
	v_add_co_u32_e32 v76, vcc, s3, v12
	s_mov_b32 s3, 0xaa17000
	s_nop 0
	v_addc_co_u32_e32 v77, vcc, 0, v13, vcc
	v_add_co_u32_e32 v84, vcc, s3, v12
	s_mov_b32 s3, 0xaa18000
	s_nop 0
	v_addc_co_u32_e32 v85, vcc, 0, v13, vcc
	global_load_dword v75, v[84:85], off offset:-4096
	global_load_ushort v81, v[14:15], off offset:1664
	s_nop 0
	global_load_dword v77, v[76:77], off offset:2048
	s_nop 0
	global_load_ushort v82, v[14:15], off offset:1792
	global_load_dword v78, v[84:85], off
	global_load_ushort v83, v[14:15], off offset:1920
	global_load_dword v79, v[84:85], off offset:2048
	global_load_ushort v76, v[14:15], off offset:2048
	v_add_co_u32_e32 v84, vcc, s3, v12
	s_mov_b32 s3, 0xaa19000
	s_nop 0
	v_addc_co_u32_e32 v85, vcc, 0, v13, vcc
	v_add_co_u32_e32 v92, vcc, s3, v12
	s_mov_b32 s3, 0xaa1a000
	s_nop 0
	v_addc_co_u32_e32 v93, vcc, 0, v13, vcc
	v_add_co_u32_e32 v94, vcc, s3, v12
	s_mov_b32 s3, 0xaa1b000
	s_nop 0
	v_addc_co_u32_e32 v95, vcc, 0, v13, vcc
	v_add_co_u32_e32 v96, vcc, s3, v12
	s_mov_b32 s3, 0xaa1c000
	s_nop 0
	v_addc_co_u32_e32 v97, vcc, 0, v13, vcc
	v_add_co_u32_e32 v104, vcc, s3, v12
	s_mov_b32 s3, 0xaa1d000
	s_nop 0
	v_addc_co_u32_e32 v105, vcc, 0, v13, vcc
	v_add_co_u32_e32 v124, vcc, s3, v12
	s_mov_b32 s3, 0xaa1e000
	s_nop 0
	v_addc_co_u32_e32 v125, vcc, 0, v13, vcc
	v_add_co_u32_e32 v126, vcc, s3, v12
	s_mov_b32 s3, 0xaa1f000
	s_nop 0
	v_addc_co_u32_e32 v127, vcc, 0, v13, vcc
	v_add_co_u32_e32 v132, vcc, s3, v12
	s_mov_b32 s3, 0xca80000
	s_nop 0
	v_addc_co_u32_e32 v133, vcc, 0, v13, vcc
	global_load_dword v90, v[92:93], off offset:-4096
	global_load_ushort v89, v[14:15], off offset:2176
	global_load_dword v88, v[84:85], off offset:2048
	global_load_ushort v87, v[14:15], off offset:2304
	global_load_dword v86, v[92:93], off
	s_nop 0
	global_load_ushort v85, v[14:15], off offset:2432
	global_load_dword v84, v[92:93], off offset:2048
	global_load_ushort v80, v[14:15], off offset:2560
	s_nop 0
	global_load_dword v92, v[96:97], off offset:-4096
	global_load_ushort v98, v[14:15], off offset:2688
	s_nop 0
	global_load_dword v94, v[94:95], off offset:2048
	s_nop 0
	global_load_ushort v99, v[14:15], off offset:2816
	global_load_dword v95, v[96:97], off
	global_load_ushort v100, v[14:15], off offset:2944
	s_nop 0
	global_load_dword v96, v[96:97], off offset:2048
	s_nop 0
	global_load_ushort v93, v[14:15], off offset:3072
	global_load_dword v111, v[124:125], off offset:-4096
	global_load_ushort v109, v[14:15], off offset:3200
	global_load_dword v107, v[104:105], off offset:2048
	s_nop 0
	global_load_ushort v105, v[14:15], off offset:3328
	global_load_dword v104, v[124:125], off
	global_load_ushort v102, v[14:15], off offset:3456
	global_load_dword v101, v[124:125], off offset:2048
	global_load_ushort v97, v[14:15], off offset:3584
	s_nop 0
	global_load_dword v124, v[132:133], off offset:-4096
	global_load_ushort v122, v[14:15], off offset:3712
	global_load_dword v125, v[126:127], off offset:2048
	s_nop 0
	global_load_ushort v127, v[14:15], off offset:3840
	global_load_dword v126, v[132:133], off
	global_load_ushort v128, v[14:15], off offset:3968
	global_load_dword v129, v[132:133], off offset:2048
	v_add_co_u32_e32 v14, vcc, s3, v10
	v_cvt_pk_bf16_f32 v131, v130, s0
	s_nop 0
	v_addc_co_u32_e32 v15, vcc, 0, v11, vcc
	global_store_short v[14:15], v131, off sc0 sc1
	v_lshlrev_b32_e32 v131, 16, v103
	v_fmac_f32_e32 v131, v16, v130
	v_cvt_pk_bf16_f32 v130, v131, s0
	global_store_short v[14:15], v130, off offset:128 sc0 sc1
	v_and_b32_e32 v130, 0xffff0000, v103
	v_fmac_f32_e32 v130, v17, v131
	v_cvt_pk_bf16_f32 v131, v130, s0
	global_store_short v[14:15], v131, off offset:256 sc0 sc1
	v_lshlrev_b32_e32 v131, 16, v106
	s_waitcnt vmcnt(62)
; #define SLOAD(uq, dq, c0) _Pragma("unroll") for (int i = 0; i < 32; ++i) { uq[i] = U[(size_t)((c0) + i) * 64]; dq[i] = dv[(size_t)((c0) + i) * 512]; }
; #define SSCAN(uq, dq, c0) _Pragma("unroll") for (int i = 0; i < 32; ++i) { ST[(size_t)((c0) + i) * 64] = (u16)pk_bf16(st, 0.f); st = dq[i] * st + bf2f(uq[i]); }
; DI void scan_phase(const Params& p) {
;     ...
;     SLOAD(ua, da, 0)
;     for (int c0 = 0; c0 < 256; c0 += 64) {
;       SLOAD(ub, db, c0 + 32)
;       SSCAN(ua, da, c0)
;       if (c0 + 64 < 256) SLOAD(ua, da, c0 + 64)
;       SSCAN(ub, db, c0 + 32)
	v_fmac_f32_e32 v131, v19, v130
	v_cvt_pk_bf16_f32 v130, v131, s0
	global_store_short v[14:15], v130, off offset:384 sc0 sc1
	v_and_b32_e32 v130, 0xffff0000, v106
	v_fmac_f32_e32 v130, v18, v131
	v_cvt_pk_bf16_f32 v131, v130, s0
	global_store_short v[14:15], v131, off offset:512 sc0 sc1
	v_lshlrev_b32_e32 v131, 16, v108
	v_fmac_f32_e32 v131, v20, v130
	v_cvt_pk_bf16_f32 v130, v131, s0
	global_store_short v[14:15], v130, off offset:640 sc0 sc1
	v_and_b32_e32 v130, 0xffff0000, v108
	v_fmac_f32_e32 v130, v22, v131
	v_cvt_pk_bf16_f32 v131, v130, s0
	global_store_short v[14:15], v131, off offset:768 sc0 sc1
	v_lshlrev_b32_e32 v131, 16, v110
	v_fmac_f32_e32 v131, v25, v130
	v_cvt_pk_bf16_f32 v130, v131, s0
	global_store_short v[14:15], v130, off offset:896 sc0 sc1
	v_and_b32_e32 v130, 0xffff0000, v110
	v_fmac_f32_e32 v130, v24, v131
	v_cvt_pk_bf16_f32 v131, v130, s0
	global_store_short v[14:15], v131, off offset:1024 sc0 sc1
	v_lshlrev_b32_e32 v131, 16, v112
	v_fmac_f32_e32 v131, v30, v130
	v_cvt_pk_bf16_f32 v130, v131, s0
	global_store_short v[14:15], v130, off offset:1152 sc0 sc1
	v_and_b32_e32 v130, 0xffff0000, v112
	v_fmac_f32_e32 v130, v21, v131
	v_cvt_pk_bf16_f32 v131, v130, s0
	global_store_short v[14:15], v131, off offset:1280 sc0 sc1
	v_lshlrev_b32_e32 v131, 16, v113
	v_fmac_f32_e32 v131, v23, v130
	v_cvt_pk_bf16_f32 v130, v131, s0
	global_store_short v[14:15], v130, off offset:1408 sc0 sc1
	v_and_b32_e32 v130, 0xffff0000, v113
	v_fmac_f32_e32 v130, v28, v131
	v_cvt_pk_bf16_f32 v131, v130, s0
	global_store_short v[14:15], v131, off offset:1536 sc0 sc1
	v_lshlrev_b32_e32 v131, 16, v114
	v_fmac_f32_e32 v131, v26, v130
	v_cvt_pk_bf16_f32 v130, v131, s0
	global_store_short v[14:15], v130, off offset:1664 sc0 sc1
	v_and_b32_e32 v130, 0xffff0000, v114
	v_fmac_f32_e32 v130, v27, v131
	v_cvt_pk_bf16_f32 v131, v130, s0
	global_store_short v[14:15], v131, off offset:1792 sc0 sc1
	v_lshlrev_b32_e32 v131, 16, v115
	v_fmac_f32_e32 v131, v29, v130
	v_cvt_pk_bf16_f32 v130, v131, s0
	global_store_short v[14:15], v130, off offset:1920 sc0 sc1
	v_and_b32_e32 v130, 0xffff0000, v115
	v_fmac_f32_e32 v130, v34, v131
	v_cvt_pk_bf16_f32 v131, v130, s0
	global_store_short v[14:15], v131, off offset:2048 sc0 sc1
	v_lshlrev_b32_e32 v131, 16, v116
	v_fmac_f32_e32 v131, v31, v130
	v_cvt_pk_bf16_f32 v130, v131, s0
	global_store_short v[14:15], v130, off offset:2176 sc0 sc1
	v_and_b32_e32 v130, 0xffff0000, v116
	v_fmac_f32_e32 v130, v32, v131
	v_cvt_pk_bf16_f32 v131, v130, s0
	global_store_short v[14:15], v131, off offset:2304 sc0 sc1
	v_lshlrev_b32_e32 v131, 16, v117
	v_fmac_f32_e32 v131, v35, v130
	v_cvt_pk_bf16_f32 v130, v131, s0
	global_store_short v[14:15], v130, off offset:2432 sc0 sc1
	v_and_b32_e32 v130, 0xffff0000, v117
	v_fmac_f32_e32 v130, v37, v131
	v_cvt_pk_bf16_f32 v131, v130, s0
	global_store_short v[14:15], v131, off offset:2560 sc0 sc1
	v_lshlrev_b32_e32 v131, 16, v118
	v_fmac_f32_e32 v131, v38, v130
	v_cvt_pk_bf16_f32 v130, v131, s0
	global_store_short v[14:15], v130, off offset:2688 sc0 sc1
	v_and_b32_e32 v130, 0xffff0000, v118
	v_fmac_f32_e32 v130, v39, v131
	v_cvt_pk_bf16_f32 v131, v130, s0
	global_store_short v[14:15], v131, off offset:2816 sc0 sc1
	v_lshlrev_b32_e32 v131, 16, v119
	v_fmac_f32_e32 v131, v40, v130
	v_cvt_pk_bf16_f32 v130, v131, s0
	global_store_short v[14:15], v130, off offset:2944 sc0 sc1
	v_and_b32_e32 v130, 0xffff0000, v119
	v_fmac_f32_e32 v130, v41, v131
	v_cvt_pk_bf16_f32 v131, v130, s0
	global_store_short v[14:15], v131, off offset:3072 sc0 sc1
	v_lshlrev_b32_e32 v131, 16, v120
	v_fmac_f32_e32 v131, v51, v130
	v_cvt_pk_bf16_f32 v130, v131, s0
	global_store_short v[14:15], v130, off offset:3200 sc0 sc1
	v_and_b32_e32 v130, 0xffff0000, v120
	v_fmac_f32_e32 v130, v52, v131
	v_cvt_pk_bf16_f32 v131, v130, s0
	global_store_short v[14:15], v131, off offset:3328 sc0 sc1
	v_lshlrev_b32_e32 v131, 16, v121
	v_fmac_f32_e32 v131, v61, v130
	v_cvt_pk_bf16_f32 v130, v131, s0
	global_store_short v[14:15], v130, off offset:3456 sc0 sc1
	v_and_b32_e32 v130, 0xffff0000, v121
	v_fmac_f32_e32 v130, v71, v131
	v_cvt_pk_bf16_f32 v131, v130, s0
	global_store_short v[14:15], v131, off offset:3584 sc0 sc1
	v_lshlrev_b32_e32 v131, 16, v123
	v_fmac_f32_e32 v131, v72, v130
	v_and_b32_e32 v132, 0xffff0000, v123
	v_cvt_pk_bf16_f32 v130, v131, s0
	v_fmac_f32_e32 v132, v74, v131
	global_store_short v[14:15], v130, off offset:3712 sc0 sc1
	v_cvt_pk_bf16_f32 v130, v132, s0
	global_store_short v[14:15], v130, off offset:3840 sc0 sc1
	v_lshlrev_b32_e32 v130, 16, v36
	v_fmac_f32_e32 v130, v91, v132
	s_cmpk_gt_u32 s2, 0xbf
	v_cvt_pk_bf16_f32 v131, v130, s0
	s_cselect_b64 s[28:29], -1, 0
	s_cmpk_lt_u32 s2, 0xc0
	global_store_short v[14:15], v131, off offset:3968 sc0 sc1
	s_cbranch_scc1 .LBB0_850
	v_mov_b32_e32 v12, v33
	v_mov_b32_e32 v13, v36
	s_branch .LBB0_851

; DI unsigned pk_bf16(float lo, float hi) { f32x2_t v = {lo, hi}; return __builtin_bit_cast(unsigned, __builtin_convertvector(v, bf16x2_t)); }
; DI void cvt_rows(const float* __restrict__ src, u16* __restrict__ dst, size_t n) {
;     ...
;   for (; i + 3 * T < nv; i += 4 * T) {
;     f32x4 a[4], b[4];
; #pragma unroll
;     for (int u = 0; u < 4; ++u) { a[u] = *(const f32x4*)(src + (i + u * T) * 8); b[u] = *(const f32x4*)(src + (i + u * T) * 8 + 4); }
; #pragma unroll
;     for (int u = 0; u < 4; ++u) {
;       u32x4 o; o[0] = pk_bf16(a[u][0], a[u][1]); o[1] = pk_bf16(a[u][2], a[u][3]); o[2] = pk_bf16(b[u][0], b[u][1]); o[3] = pk_bf16(b[u][2], b[u][3]);
;       *(u32x4*)(dst + (i + u * T) * 8) = o;
;     }
;   }
.LBB0_1404:
	global_load_dwordx4 v[12:15], v[10:11], off offset:16
	global_load_dwordx4 v[16:19], v[10:11], off
	v_lshl_add_u64 v[28:29], v[10:11], 0, s[44:45]
	global_load_dwordx4 v[20:23], v[28:29], off offset:16
	global_load_dwordx4 v[24:27], v[28:29], off
	v_lshl_add_u64 v[36:37], v[28:29], 0, s[44:45]
	global_load_dwordx4 v[28:31], v[36:37], off offset:16
	global_load_dwordx4 v[32:35], v[36:37], off
	v_lshl_add_u64 v[40:41], v[36:37], 0, s[44:45]
	global_load_dwordx4 v[36:39], v[40:41], off offset:16
	s_nop 0
	global_load_dwordx4 v[40:43], v[40:41], off
	s_add_u32 s2, s40, s40
	s_addc_u32 s3, s41, s41
	s_add_u32 s2, s2, s2
	s_addc_u32 s3, s3, s3
	v_lshl_add_u64 v[0:1], s[2:3], 0, v[0:1]
	v_lshl_add_u64 v[10:11], v[10:11], 0, s[42:43]
	s_waitcnt vmcnt(6)
	v_cvt_pk_bf16_f32 v16, v16, v17
	v_cvt_pk_bf16_f32 v17, v18, v19
	v_cvt_pk_bf16_f32 v18, v12, v13
	v_cvt_pk_bf16_f32 v19, v14, v15
	v_lshl_add_u64 v[12:13], s[28:29], 0, v[2:3]
	global_store_dwordx4 v[12:13], v[16:19], off sc0 sc1
	s_waitcnt vmcnt(5)
	v_cvt_pk_bf16_f32 v12, v24, v25
	v_cvt_pk_bf16_f32 v13, v26, v27
	v_cvt_pk_bf16_f32 v14, v20, v21
	v_cvt_pk_bf16_f32 v15, v22, v23
	v_lshl_add_u64 v[16:17], s[28:29], 0, v[8:9]
	global_store_dwordx4 v[16:17], v[12:15], off sc0 sc1
	v_lshl_add_u64 v[16:17], s[28:29], 0, v[4:5]
	s_waitcnt vmcnt(4)
	v_cvt_pk_bf16_f32 v12, v32, v33
	v_cvt_pk_bf16_f32 v13, v34, v35
	v_cvt_pk_bf16_f32 v14, v28, v29
	v_cvt_pk_bf16_f32 v15, v30, v31
	global_store_dwordx4 v[16:17], v[12:15], off sc0 sc1
	v_lshl_add_u64 v[16:17], s[28:29], 0, v[6:7]
	s_add_u32 s28, s28, s36
	s_waitcnt vmcnt(3)
	v_cvt_pk_bf16_f32 v12, v40, v41
	v_cvt_pk_bf16_f32 v13, v42, v43
	v_cvt_pk_bf16_f32 v14, v36, v37
	v_cvt_pk_bf16_f32 v15, v38, v39
	global_store_dwordx4 v[16:17], v[12:15], off sc0 sc1
	s_addc_u32 s29, s29, s37
	s_nop 0
	v_lshl_add_u64 v[12:13], s[38:39], 0, v[0:1]
	v_cmp_lt_u64_e32 vcc, s[46:47], v[12:13]
	s_or_b64 s[22:23], vcc, s[22:23]
	s_andn2_b64 exec, exec, s[22:23]
	s_cbranch_execnz .LBB0_1404
	s_or_b64 exec, exec, s[22:23]

; DI unsigned pk_bf16(float lo, float hi) { f32x2_t v = {lo, hi}; return __builtin_bit_cast(unsigned, __builtin_convertvector(v, bf16x2_t)); }
; DI void cvt_rows(const float* __restrict__ src, u16* __restrict__ dst, size_t n) {
;     ...
;   for (; i < nv; i += T) {
;     const f32x4 a = *(const f32x4*)(src + i * 8), b = *(const f32x4*)(src + i * 8 + 4);
;     u32x4 o; o[0] = pk_bf16(a[0], a[1]); o[1] = pk_bf16(a[2], a[3]); o[2] = pk_bf16(b[0], b[1]); o[3] = pk_bf16(b[2], b[3]);
;     *(u32x4*)(dst + i * 8) = o;
;   }
.LBB0_1408:
	global_load_dwordx4 v[6:9], v[2:3], off
	global_load_dwordx4 v[10:13], v[2:3], off offset:16
	v_lshl_add_u64 v[0:1], v[0:1], 0, s[40:41]
	v_cmp_lt_u64_e32 vcc, s[38:39], v[0:1]
	v_lshl_add_u64 v[2:3], v[2:3], 0, s[28:29]
	s_or_b64 s[22:23], vcc, s[22:23]
	s_waitcnt vmcnt(1)
	v_cvt_pk_bf16_f32 v6, v6, v7
	v_cvt_pk_bf16_f32 v7, v8, v9
	s_waitcnt vmcnt(0)
	v_cvt_pk_bf16_f32 v8, v10, v11
	v_cvt_pk_bf16_f32 v9, v12, v13
	global_store_dwordx4 v[4:5], v[6:9], off sc0 sc1
	v_lshl_add_u64 v[4:5], v[4:5], 0, s[36:37]
	s_andn2_b64 exec, exec, s[22:23]
	s_cbranch_execnz .LBB0_1408
